# gate/up fast epilogue issues the next job's decode and first-tile loads before the silu math
# baseline (speedup 1.0000x reference)
.LBB0_160:
	v_readlane_b32 s98, v255, 6
	v_readlane_b32 s99, v254, 40
	s_add_i32 s98, s0, s98
	s_cmp_ge_i32 s98, s99
	s_cbranch_scc1 .Lgu_slow
	v_mfma_f32_32x32x16_bf16 a[16:31], v[132:135], v[112:115], a[16:31]
	v_mfma_f32_32x32x16_bf16 a[32:47], v[132:135], v[80:83], a[32:47]
	v_mfma_f32_32x32x16_bf16 a[0:15], v[132:135], v[128:131], a[0:15]
	v_or_b32_e32 v129, s2, v161
	v_or_b32_e32 v128, s1, v162
	v_add_u32_e32 v133, v163, v129
	v_readlane_b32 s2, v253, 61
	v_readlane_b32 s3, v253, 62
	v_ashrrev_i32_e32 v130, 1, v128
	s_nop 0
	v_mov_b64_e32 v[128:129], s[2:3]
	s_movk_i32 s1, 0x1600
	v_mad_i64_i32 v[134:135], s[2:3], v133, s1, v[128:129]
	v_ashrrev_i32_e32 v131, 31, v130
	v_lshlrev_b64 v[130:131], 1, v[130:131]
	v_lshl_add_u64 v[96:97], v[134:135], 0, v[130:131]
	v_and_b32_e32 v192, 32, v160
	v_lshl_add_u64 v[96:97], v[96:97], 0, v[192:193]
	v_add_u32_e32 v136, 32, v133
	v_mad_i64_i32 v[136:137], s[4:5], v136, s1, v[128:129]
	v_lshl_add_u64 v[136:137], v[136:137], 0, v[130:131]
	v_lshl_add_u64 v[66:67], v[136:137], 0, v[192:193]
	v_add_u32_e32 v100, 64, v133
	v_mad_i64_i32 v[100:101], s[4:5], v100, s1, v[128:129]
	v_lshl_add_u64 v[100:101], v[100:101], 0, v[130:131]
	v_lshl_add_u64 v[64:65], v[100:101], 0, v[192:193]
	v_mov_b32_e32 v164, v96
	v_mov_b32_e32 v165, v97
	v_mov_b32_e32 v166, v66
	v_mov_b32_e32 v167, v67
	v_mov_b32_e32 v168, v64
	v_mov_b32_e32 v169, v65
	s_mov_b32 s0, s98
	v_mov_b32_e32 v214, 0x4000
	s_abs_i32 s2, s0
	v_readlane_b32 s3, v254, 44
	s_mul_hi_u32 s3, s2, s3
	v_readlane_b32 s6, v254, 43
	s_mul_i32 s4, s3, s6
	s_sub_i32 s2, s2, s4
	s_ashr_i32 s1, s0, 31
	s_add_i32 s4, s3, 1
	s_sub_i32 s5, s2, s6
	s_cmp_ge_u32 s2, s6
	s_cselect_b32 s3, s4, s3
	s_cselect_b32 s2, s5, s2
	s_add_i32 s4, s3, 1
	s_cmp_ge_u32 s2, s6
	s_cselect_b32 s2, s4, s3
	s_xor_b32 s2, s2, s1
	s_sub_i32 s1, s2, s1
	s_lshr_b32 s2, s0, 31
	s_add_i32 s2, s0, s2
	s_ashr_i32 s3, s2, 1
	s_abs_i32 s3, s3
	v_readlane_b32 s5, v254, 46
	s_mul_hi_u32 s5, s3, s5
	v_readlane_b32 s6, v254, 45
	s_mul_i32 s5, s5, s6
	s_and_b32 s4, s2, 0xfffffe
	s_sub_i32 s3, s3, s5
	s_sub_i32 s4, s0, s4
	s_ashr_i32 s2, s2, 31
	s_sub_i32 s5, s3, s6
	s_cmp_ge_u32 s3, s6
	s_cselect_b32 s3, s5, s3
	s_sub_i32 s5, s3, s6
	s_cmp_ge_u32 s3, s6
	s_cselect_b32 s3, s5, s3
	s_xor_b32 s3, s3, s2
	s_sub_i32 s2, s3, s2
	v_readlane_b32 s3, v254, 39
	s_add_i32 s2, s3, s2
	s_lshl_b32 s1, s1, 9
	s_lshl_b32 s3, s4, 8
	v_mov_b32_e32 v160, v208
	s_add_i32 s1, s1, s3
	v_readlane_b32 s4, v253, 30
	v_ashrrev_i32_e32 v4, 2, v160
	v_add_u32_e32 v0, s1, v4
	v_ashrrev_i32_e32 v1, 31, v0
	v_lshlrev_b64 v[0:1], 11, v[0:1]
	v_readlane_b32 s5, v253, 31
	v_lshlrev_b32_e32 v5, 4, v160
	s_mulk_i32 s2, 0xc0
	v_lshl_add_u64 v[0:1], s[4:5], 0, v[0:1]
	v_and_b32_e32 v192, 48, v5
	v_lshl_add_u64 v[96:97], v[0:1], 0, v[192:193]
	v_add_u32_e32 v0, s2, v4
	v_ashrrev_i32_e32 v1, 31, v0
	v_readlane_b32 s4, v253, 16
	s_mov_b32 s3, 0x20000
	v_lshlrev_b64 v[0:1], 11, v[0:1]
	v_readlane_b32 s5, v253, 17
	v_add_co_u32_e32 v8, vcc, s3, v96
	s_nop 0
	v_lshl_add_u64 v[0:1], s[4:5], 0, v[0:1]
	v_addc_co_u32_e32 v9, vcc, 0, v97, vcc
	s_mov_b32 s4, 0x40000
	v_add_co_u32_e32 v12, vcc, s4, v96
	v_lshl_add_u64 v[98:99], v[0:1], 0, v[192:193]
	s_nop 0
	v_addc_co_u32_e32 v13, vcc, 0, v97, vcc
	v_add_co_u32_e32 v16, vcc, s75, v96
	v_bfe_u32 v6, v160, 5, 1
	s_nop 0
	v_addc_co_u32_e32 v17, vcc, 0, v97, vcc
	v_lshrrev_b32_e32 v7, 2, v160
	v_bfe_u32 v10, v160, 2, 2
	v_add_co_u32_e32 v24, vcc, s3, v98
	v_lshlrev_b32_e32 v11, 1, v160
	v_bitop3_b32 v7, v6, v7, 3 bitop3:0x78
	v_bitop3_b32 v6, v6, v10, 2 bitop3:0x36
	v_and_b32_e32 v10, 0xffffffe0, v4
	v_addc_co_u32_e32 v25, vcc, 0, v99, vcc
	v_and_b32_e32 v161, 31, v160
	v_and_b32_e32 v162, 0x80, v11
	v_lshl_add_u32 v163, v10, 1, v10
	v_add_co_u32_e32 v28, vcc, s4, v98
	v_or_b32_e32 v11, v162, v161
	v_or_b32_e32 v10, v163, v161
	global_load_dwordx4 v[0:3], v[96:97], off
	global_load_dwordx4 v[32:35], v[8:9], off
	global_load_dwordx4 v[36:39], v[12:13], off
	global_load_dwordx4 v[40:43], v[16:17], off
	global_load_dwordx4 v[44:47], v[98:99], off
	v_addc_co_u32_e32 v29, vcc, 0, v99, vcc
	v_bitop3_b32 v5, v5, 48, v160 bitop3:0x48
	v_lshlrev_b32_e32 v11, 6, v11
	v_lshlrev_b32_e32 v7, 4, v7
	v_lshlrev_b32_e32 v6, 4, v6
	v_lshl_add_u32 v10, v10, 6, v214
	global_load_dwordx4 v[48:51], v[24:25], off
	global_load_dwordx4 v[52:55], v[28:29], off
	v_or_b32_e32 v110, v11, v7
	v_or_b32_e32 v111, v11, v6
	v_or_b32_e32 v116, v10, v7
	v_or_b32_e32 v117, v10, v6
	v_lshl_or_b32 v118, v4, 6, v5
	global_load_dwordx4 v[4:7], v[96:97], off offset:64
	s_nop 0
	global_load_dwordx4 v[8:11], v[8:9], off offset:64
	s_nop 0
	global_load_dwordx4 v[12:15], v[12:13], off offset:64
	s_nop 0
	global_load_dwordx4 v[16:19], v[16:17], off offset:64
	s_nop 0
	global_load_dwordx4 v[20:23], v[98:99], off offset:64
	s_nop 0
	global_load_dwordx4 v[24:27], v[24:25], off offset:64
	s_nop 0
	global_load_dwordx4 v[28:31], v[28:29], off offset:64
	v_mov_b32_e32 v186, 0xbfb8aa3b
	v_mov_b32_e32 v187, 0xbfb8aa3b
	v_accvgpr_read_b32 v56, a80
	v_accvgpr_read_b32 v57, a81
	v_accvgpr_read_b32 v58, a82
	v_accvgpr_read_b32 v59, a83
	v_accvgpr_read_b32 v60, a84
	v_accvgpr_read_b32 v61, a85
	v_accvgpr_read_b32 v62, a86
	v_accvgpr_read_b32 v63, a87
	v_accvgpr_read_b32 v64, a88
	v_accvgpr_read_b32 v65, a89
	v_accvgpr_read_b32 v66, a90
	v_accvgpr_read_b32 v67, a91
	v_accvgpr_read_b32 v68, a92
	v_accvgpr_read_b32 v69, a93
	v_accvgpr_read_b32 v70, a94
	v_accvgpr_read_b32 v71, a95
	v_pk_mul_f32 v[120:121], v[56:57], v[186:187]
	v_pk_mul_f32 v[122:123], v[58:59], v[186:187]
	v_pk_mul_f32 v[124:125], v[60:61], v[186:187]
	v_pk_mul_f32 v[126:127], v[62:63], v[186:187]
	v_pk_mul_f32 v[128:129], v[64:65], v[186:187]
	v_pk_mul_f32 v[130:131], v[66:67], v[186:187]
	v_pk_mul_f32 v[132:133], v[68:69], v[186:187]
	v_pk_mul_f32 v[134:135], v[70:71], v[186:187]
	v_accvgpr_read_b32 v72, a96
	v_accvgpr_read_b32 v73, a97
	v_accvgpr_read_b32 v74, a98
	v_accvgpr_read_b32 v75, a99
	v_accvgpr_read_b32 v76, a100
	v_accvgpr_read_b32 v77, a101
	v_accvgpr_read_b32 v78, a102
	v_accvgpr_read_b32 v79, a103
	v_accvgpr_read_b32 v80, a104
	v_accvgpr_read_b32 v81, a105
	v_accvgpr_read_b32 v82, a106
	v_accvgpr_read_b32 v83, a107
	v_accvgpr_read_b32 v84, a108
	v_accvgpr_read_b32 v85, a109
	v_accvgpr_read_b32 v86, a110
	v_accvgpr_read_b32 v87, a111
	v_exp_f32_e32 v120, v120
	v_exp_f32_e32 v121, v121
	v_exp_f32_e32 v122, v122
	v_exp_f32_e32 v123, v123
	v_exp_f32_e32 v124, v124
	v_exp_f32_e32 v125, v125
	v_exp_f32_e32 v126, v126
	v_exp_f32_e32 v127, v127
	v_exp_f32_e32 v128, v128
	v_exp_f32_e32 v129, v129
	v_exp_f32_e32 v130, v130
	v_exp_f32_e32 v131, v131
	v_exp_f32_e32 v132, v132
	v_exp_f32_e32 v133, v133
	v_exp_f32_e32 v134, v134
	v_exp_f32_e32 v135, v135
	s_nop 0
	v_pk_add_f32 v[120:121], v[120:121], 1.0 op_sel_hi:[1,0]
	v_pk_add_f32 v[122:123], v[122:123], 1.0 op_sel_hi:[1,0]
	v_pk_add_f32 v[124:125], v[124:125], 1.0 op_sel_hi:[1,0]
	v_pk_add_f32 v[126:127], v[126:127], 1.0 op_sel_hi:[1,0]
	v_pk_add_f32 v[128:129], v[128:129], 1.0 op_sel_hi:[1,0]
	v_pk_add_f32 v[130:131], v[130:131], 1.0 op_sel_hi:[1,0]
	v_pk_add_f32 v[132:133], v[132:133], 1.0 op_sel_hi:[1,0]
	v_pk_add_f32 v[134:135], v[134:135], 1.0 op_sel_hi:[1,0]
	v_rcp_f32_e32 v120, v120
	v_rcp_f32_e32 v121, v121
	v_rcp_f32_e32 v122, v122
	v_rcp_f32_e32 v123, v123
	v_rcp_f32_e32 v124, v124
	v_rcp_f32_e32 v125, v125
	v_rcp_f32_e32 v126, v126
	v_rcp_f32_e32 v127, v127
	v_rcp_f32_e32 v128, v128
	v_rcp_f32_e32 v129, v129
	v_rcp_f32_e32 v130, v130
	v_rcp_f32_e32 v131, v131
	v_rcp_f32_e32 v132, v132
	v_rcp_f32_e32 v133, v133
	v_rcp_f32_e32 v134, v134
	v_rcp_f32_e32 v135, v135
	s_nop 0
	v_pk_mul_f32 v[120:121], v[56:57], v[120:121]
	v_pk_mul_f32 v[122:123], v[58:59], v[122:123]
	v_pk_mul_f32 v[124:125], v[60:61], v[124:125]
	v_pk_mul_f32 v[126:127], v[62:63], v[126:127]
	v_pk_mul_f32 v[128:129], v[64:65], v[128:129]
	v_pk_mul_f32 v[130:131], v[66:67], v[130:131]
	v_pk_mul_f32 v[132:133], v[68:69], v[132:133]
	v_pk_mul_f32 v[134:135], v[70:71], v[134:135]
	v_pk_mul_f32 v[120:121], v[120:121], v[72:73]
	v_pk_mul_f32 v[122:123], v[122:123], v[74:75]
	v_pk_mul_f32 v[124:125], v[124:125], v[76:77]
	v_pk_mul_f32 v[126:127], v[126:127], v[78:79]
	v_pk_mul_f32 v[128:129], v[128:129], v[80:81]
	v_pk_mul_f32 v[130:131], v[130:131], v[82:83]
	v_pk_mul_f32 v[132:133], v[132:133], v[84:85]
	v_pk_mul_f32 v[134:135], v[134:135], v[86:87]
	v_cvt_pk_bf16_f32 v88, v120, v121
	v_cvt_pk_bf16_f32 v89, v122, v123
	v_cvt_pk_bf16_f32 v92, v124, v125
	v_cvt_pk_bf16_f32 v93, v126, v127
	v_cvt_pk_bf16_f32 v90, v128, v129
	v_cvt_pk_bf16_f32 v91, v130, v131
	v_cvt_pk_bf16_f32 v94, v132, v133
	v_cvt_pk_bf16_f32 v95, v134, v135
	s_nop 1
	v_permlane32_swap_b32_e32 v88, v90
	v_permlane32_swap_b32_e32 v89, v91
	v_permlane32_swap_b32_e32 v92, v94
	v_permlane32_swap_b32_e32 v93, v95
	s_nop 1
	global_store_dwordx4 v[164:165], v[88:91], off
	global_store_dwordx4 v[164:165], v[92:95], off offset:16
	v_accvgpr_read_b32 v136, a48
	v_accvgpr_read_b32 v137, a49
	v_accvgpr_read_b32 v138, a50
	v_accvgpr_read_b32 v139, a51
	v_accvgpr_read_b32 v140, a52
	v_accvgpr_read_b32 v141, a53
	v_accvgpr_read_b32 v142, a54
	v_accvgpr_read_b32 v143, a55
	v_accvgpr_read_b32 v144, a56
	v_accvgpr_read_b32 v145, a57
	v_accvgpr_read_b32 v146, a58
	v_accvgpr_read_b32 v147, a59
	v_accvgpr_read_b32 v148, a60
	v_accvgpr_read_b32 v149, a61
	v_accvgpr_read_b32 v150, a62
	v_accvgpr_read_b32 v151, a63
	v_pk_mul_f32 v[232:233], v[136:137], v[186:187]
	v_pk_mul_f32 v[234:235], v[138:139], v[186:187]
	v_pk_mul_f32 v[236:237], v[140:141], v[186:187]
	v_pk_mul_f32 v[238:239], v[142:143], v[186:187]
	v_pk_mul_f32 v[240:241], v[144:145], v[186:187]
	v_pk_mul_f32 v[242:243], v[146:147], v[186:187]
	v_pk_mul_f32 v[244:245], v[148:149], v[186:187]
	v_pk_mul_f32 v[246:247], v[150:151], v[186:187]
	v_accvgpr_read_b32 v170, a112
	v_accvgpr_read_b32 v171, a113
	v_accvgpr_read_b32 v172, a114
	v_accvgpr_read_b32 v173, a115
	v_accvgpr_read_b32 v174, a116
	v_accvgpr_read_b32 v175, a117
	v_accvgpr_read_b32 v176, a118
	v_accvgpr_read_b32 v177, a119
	v_accvgpr_read_b32 v178, a120
	v_accvgpr_read_b32 v179, a121
	v_accvgpr_read_b32 v180, a122
	v_accvgpr_read_b32 v181, a123
	v_accvgpr_read_b32 v182, a124
	v_accvgpr_read_b32 v183, a125
	v_accvgpr_read_b32 v184, a126
	v_accvgpr_read_b32 v185, a127
	v_exp_f32_e32 v232, v232
	v_exp_f32_e32 v233, v233
	v_exp_f32_e32 v234, v234
	v_exp_f32_e32 v235, v235
	v_exp_f32_e32 v236, v236
	v_exp_f32_e32 v237, v237
	v_exp_f32_e32 v238, v238
	v_exp_f32_e32 v239, v239
	v_exp_f32_e32 v240, v240
	v_exp_f32_e32 v241, v241
	v_exp_f32_e32 v242, v242
	v_exp_f32_e32 v243, v243
	v_exp_f32_e32 v244, v244
	v_exp_f32_e32 v245, v245
	v_exp_f32_e32 v246, v246
	v_exp_f32_e32 v247, v247
	s_nop 0
	v_pk_add_f32 v[232:233], v[232:233], 1.0 op_sel_hi:[1,0]
	v_pk_add_f32 v[234:235], v[234:235], 1.0 op_sel_hi:[1,0]
	v_pk_add_f32 v[236:237], v[236:237], 1.0 op_sel_hi:[1,0]
	v_pk_add_f32 v[238:239], v[238:239], 1.0 op_sel_hi:[1,0]
	v_pk_add_f32 v[240:241], v[240:241], 1.0 op_sel_hi:[1,0]
	v_pk_add_f32 v[242:243], v[242:243], 1.0 op_sel_hi:[1,0]
	v_pk_add_f32 v[244:245], v[244:245], 1.0 op_sel_hi:[1,0]
	v_pk_add_f32 v[246:247], v[246:247], 1.0 op_sel_hi:[1,0]
	v_rcp_f32_e32 v232, v232
	v_rcp_f32_e32 v233, v233
	v_rcp_f32_e32 v234, v234
	v_rcp_f32_e32 v235, v235
	v_rcp_f32_e32 v236, v236
	v_rcp_f32_e32 v237, v237
	v_rcp_f32_e32 v238, v238
	v_rcp_f32_e32 v239, v239
	v_rcp_f32_e32 v240, v240
	v_rcp_f32_e32 v241, v241
	v_rcp_f32_e32 v242, v242
	v_rcp_f32_e32 v243, v243
	v_rcp_f32_e32 v244, v244
	v_rcp_f32_e32 v245, v245
	v_rcp_f32_e32 v246, v246
	v_rcp_f32_e32 v247, v247
	s_nop 0
	v_pk_mul_f32 v[232:233], v[136:137], v[232:233]
	v_pk_mul_f32 v[234:235], v[138:139], v[234:235]
	v_pk_mul_f32 v[236:237], v[140:141], v[236:237]
	v_pk_mul_f32 v[238:239], v[142:143], v[238:239]
	v_pk_mul_f32 v[240:241], v[144:145], v[240:241]
	v_pk_mul_f32 v[242:243], v[146:147], v[242:243]
	v_pk_mul_f32 v[244:245], v[148:149], v[244:245]
	v_pk_mul_f32 v[246:247], v[150:151], v[246:247]
	v_pk_mul_f32 v[232:233], v[232:233], v[170:171]
	v_pk_mul_f32 v[234:235], v[234:235], v[172:173]
	v_pk_mul_f32 v[236:237], v[236:237], v[174:175]
	v_pk_mul_f32 v[238:239], v[238:239], v[176:177]
	v_pk_mul_f32 v[240:241], v[240:241], v[178:179]
	v_pk_mul_f32 v[242:243], v[242:243], v[180:181]
	v_pk_mul_f32 v[244:245], v[244:245], v[182:183]
	v_pk_mul_f32 v[246:247], v[246:247], v[184:185]
	v_cvt_pk_bf16_f32 v152, v232, v233
	v_cvt_pk_bf16_f32 v153, v234, v235
	v_cvt_pk_bf16_f32 v156, v236, v237
	v_cvt_pk_bf16_f32 v157, v238, v239
	v_cvt_pk_bf16_f32 v154, v240, v241
	v_cvt_pk_bf16_f32 v155, v242, v243
	v_cvt_pk_bf16_f32 v158, v244, v245
	v_cvt_pk_bf16_f32 v159, v246, v247
	s_nop 1
	v_permlane32_swap_b32_e32 v152, v154
	v_permlane32_swap_b32_e32 v153, v155
	v_permlane32_swap_b32_e32 v156, v158
	v_permlane32_swap_b32_e32 v157, v159
	s_nop 1
	global_store_dwordx4 v[166:167], v[152:155], off
	global_store_dwordx4 v[166:167], v[156:159], off offset:16
	v_accvgpr_read_b32 v56, a64
	v_accvgpr_read_b32 v57, a65
	v_accvgpr_read_b32 v58, a66
	v_accvgpr_read_b32 v59, a67
	v_accvgpr_read_b32 v60, a68
	v_accvgpr_read_b32 v61, a69
	v_accvgpr_read_b32 v62, a70
	v_accvgpr_read_b32 v63, a71
	v_accvgpr_read_b32 v64, a72
	v_accvgpr_read_b32 v65, a73
	v_accvgpr_read_b32 v66, a74
	v_accvgpr_read_b32 v67, a75
	v_accvgpr_read_b32 v68, a76
	v_accvgpr_read_b32 v69, a77
	v_accvgpr_read_b32 v70, a78
	v_accvgpr_read_b32 v71, a79
	v_pk_mul_f32 v[120:121], v[56:57], v[186:187]
	v_pk_mul_f32 v[122:123], v[58:59], v[186:187]
	v_pk_mul_f32 v[124:125], v[60:61], v[186:187]
	v_pk_mul_f32 v[126:127], v[62:63], v[186:187]
	v_pk_mul_f32 v[128:129], v[64:65], v[186:187]
	v_pk_mul_f32 v[130:131], v[66:67], v[186:187]
	v_pk_mul_f32 v[132:133], v[68:69], v[186:187]
	v_pk_mul_f32 v[134:135], v[70:71], v[186:187]
	v_accvgpr_read_b32 v72, a128
	v_accvgpr_read_b32 v73, a129
	v_accvgpr_read_b32 v74, a130
	v_accvgpr_read_b32 v75, a131
	v_accvgpr_read_b32 v76, a132
	v_accvgpr_read_b32 v77, a133
	v_accvgpr_read_b32 v78, a134
	v_accvgpr_read_b32 v79, a135
	v_accvgpr_read_b32 v80, a136
	v_accvgpr_read_b32 v81, a137
	v_accvgpr_read_b32 v82, a138
	v_accvgpr_read_b32 v83, a139
	v_accvgpr_read_b32 v84, a140
	v_accvgpr_read_b32 v85, a141
	v_accvgpr_read_b32 v86, a142
	v_accvgpr_read_b32 v87, a143
	v_exp_f32_e32 v120, v120
	v_exp_f32_e32 v121, v121
	v_exp_f32_e32 v122, v122
	v_exp_f32_e32 v123, v123
	v_exp_f32_e32 v124, v124
	v_exp_f32_e32 v125, v125
	v_exp_f32_e32 v126, v126
	v_exp_f32_e32 v127, v127
	v_exp_f32_e32 v128, v128
	v_exp_f32_e32 v129, v129
	v_exp_f32_e32 v130, v130
	v_exp_f32_e32 v131, v131
	v_exp_f32_e32 v132, v132
	v_exp_f32_e32 v133, v133
	v_exp_f32_e32 v134, v134
	v_exp_f32_e32 v135, v135
	s_nop 0
	v_pk_add_f32 v[120:121], v[120:121], 1.0 op_sel_hi:[1,0]
	v_pk_add_f32 v[122:123], v[122:123], 1.0 op_sel_hi:[1,0]
	v_pk_add_f32 v[124:125], v[124:125], 1.0 op_sel_hi:[1,0]
	v_pk_add_f32 v[126:127], v[126:127], 1.0 op_sel_hi:[1,0]
	v_pk_add_f32 v[128:129], v[128:129], 1.0 op_sel_hi:[1,0]
	v_pk_add_f32 v[130:131], v[130:131], 1.0 op_sel_hi:[1,0]
	v_pk_add_f32 v[132:133], v[132:133], 1.0 op_sel_hi:[1,0]
	v_pk_add_f32 v[134:135], v[134:135], 1.0 op_sel_hi:[1,0]
	v_rcp_f32_e32 v120, v120
	v_rcp_f32_e32 v121, v121
	v_rcp_f32_e32 v122, v122
	v_rcp_f32_e32 v123, v123
	v_rcp_f32_e32 v124, v124
	v_rcp_f32_e32 v125, v125
	v_rcp_f32_e32 v126, v126
	v_rcp_f32_e32 v127, v127
	v_rcp_f32_e32 v128, v128
	v_rcp_f32_e32 v129, v129
	v_rcp_f32_e32 v130, v130
	v_rcp_f32_e32 v131, v131
	v_rcp_f32_e32 v132, v132
	v_rcp_f32_e32 v133, v133
	v_rcp_f32_e32 v134, v134
	v_rcp_f32_e32 v135, v135
	s_nop 0
	v_pk_mul_f32 v[120:121], v[56:57], v[120:121]
	v_pk_mul_f32 v[122:123], v[58:59], v[122:123]
	v_pk_mul_f32 v[124:125], v[60:61], v[124:125]
	v_pk_mul_f32 v[126:127], v[62:63], v[126:127]
	v_pk_mul_f32 v[128:129], v[64:65], v[128:129]
	v_pk_mul_f32 v[130:131], v[66:67], v[130:131]
	v_pk_mul_f32 v[132:133], v[68:69], v[132:133]
	v_pk_mul_f32 v[134:135], v[70:71], v[134:135]
	v_pk_mul_f32 v[120:121], v[120:121], v[72:73]
	v_pk_mul_f32 v[122:123], v[122:123], v[74:75]
	v_pk_mul_f32 v[124:125], v[124:125], v[76:77]
	v_pk_mul_f32 v[126:127], v[126:127], v[78:79]
	v_pk_mul_f32 v[128:129], v[128:129], v[80:81]
	v_pk_mul_f32 v[130:131], v[130:131], v[82:83]
	v_pk_mul_f32 v[132:133], v[132:133], v[84:85]
	v_pk_mul_f32 v[134:135], v[134:135], v[86:87]
	v_cvt_pk_bf16_f32 v88, v120, v121
	v_cvt_pk_bf16_f32 v89, v122, v123
	v_cvt_pk_bf16_f32 v92, v124, v125
	v_cvt_pk_bf16_f32 v93, v126, v127
	v_cvt_pk_bf16_f32 v90, v128, v129
	v_cvt_pk_bf16_f32 v91, v130, v131
	v_cvt_pk_bf16_f32 v94, v132, v133
	v_cvt_pk_bf16_f32 v95, v134, v135
	s_nop 1
	v_permlane32_swap_b32_e32 v88, v90
	v_permlane32_swap_b32_e32 v89, v91
	v_permlane32_swap_b32_e32 v92, v94
	v_permlane32_swap_b32_e32 v93, v95
	s_nop 1
	global_store_dwordx4 v[168:169], v[88:91], off
	global_store_dwordx4 v[168:169], v[92:95], off offset:16
	v_accvgpr_read_b32 v136, a144
	v_accvgpr_read_b32 v137, a145
	v_accvgpr_read_b32 v138, a146
	v_accvgpr_read_b32 v139, a147
	v_accvgpr_read_b32 v140, a148
	v_accvgpr_read_b32 v141, a149
	v_accvgpr_read_b32 v142, a150
	v_accvgpr_read_b32 v143, a151
	v_accvgpr_read_b32 v144, a152
	v_accvgpr_read_b32 v145, a153
	v_accvgpr_read_b32 v146, a154
	v_accvgpr_read_b32 v147, a155
	v_accvgpr_read_b32 v148, a156
	v_accvgpr_read_b32 v149, a157
	v_accvgpr_read_b32 v150, a158
	v_accvgpr_read_b32 v151, a159
	v_pk_mul_f32 v[232:233], v[136:137], v[186:187]
	v_pk_mul_f32 v[234:235], v[138:139], v[186:187]
	v_pk_mul_f32 v[236:237], v[140:141], v[186:187]
	v_pk_mul_f32 v[238:239], v[142:143], v[186:187]
	v_pk_mul_f32 v[240:241], v[144:145], v[186:187]
	v_pk_mul_f32 v[242:243], v[146:147], v[186:187]
	v_pk_mul_f32 v[244:245], v[148:149], v[186:187]
	v_pk_mul_f32 v[246:247], v[150:151], v[186:187]
	v_accvgpr_read_b32 v170, a32
	v_accvgpr_read_b32 v171, a33
	v_accvgpr_read_b32 v172, a34
	v_accvgpr_read_b32 v173, a35
	v_accvgpr_read_b32 v174, a36
	v_accvgpr_read_b32 v175, a37
	v_accvgpr_read_b32 v176, a38
	v_accvgpr_read_b32 v177, a39
	v_accvgpr_read_b32 v178, a40
	v_accvgpr_read_b32 v179, a41
	v_accvgpr_read_b32 v180, a42
	v_accvgpr_read_b32 v181, a43
	v_accvgpr_read_b32 v182, a44
	v_accvgpr_read_b32 v183, a45
	v_accvgpr_read_b32 v184, a46
	v_accvgpr_read_b32 v185, a47
	v_exp_f32_e32 v232, v232
	v_exp_f32_e32 v233, v233
	v_exp_f32_e32 v234, v234
	v_exp_f32_e32 v235, v235
	v_exp_f32_e32 v236, v236
	v_exp_f32_e32 v237, v237
	v_exp_f32_e32 v238, v238
	v_exp_f32_e32 v239, v239
	v_exp_f32_e32 v240, v240
	v_exp_f32_e32 v241, v241
	v_exp_f32_e32 v242, v242
	v_exp_f32_e32 v243, v243
	v_exp_f32_e32 v244, v244
	v_exp_f32_e32 v245, v245
	v_exp_f32_e32 v246, v246
	v_exp_f32_e32 v247, v247
	s_nop 0
	v_pk_add_f32 v[232:233], v[232:233], 1.0 op_sel_hi:[1,0]
	v_pk_add_f32 v[234:235], v[234:235], 1.0 op_sel_hi:[1,0]
	v_pk_add_f32 v[236:237], v[236:237], 1.0 op_sel_hi:[1,0]
	v_pk_add_f32 v[238:239], v[238:239], 1.0 op_sel_hi:[1,0]
	v_pk_add_f32 v[240:241], v[240:241], 1.0 op_sel_hi:[1,0]
	v_pk_add_f32 v[242:243], v[242:243], 1.0 op_sel_hi:[1,0]
	v_pk_add_f32 v[244:245], v[244:245], 1.0 op_sel_hi:[1,0]
	v_pk_add_f32 v[246:247], v[246:247], 1.0 op_sel_hi:[1,0]
	v_rcp_f32_e32 v232, v232
	v_rcp_f32_e32 v233, v233
	v_rcp_f32_e32 v234, v234
	v_rcp_f32_e32 v235, v235
	v_rcp_f32_e32 v236, v236
	v_rcp_f32_e32 v237, v237
	v_rcp_f32_e32 v238, v238
	v_rcp_f32_e32 v239, v239
	v_rcp_f32_e32 v240, v240
	v_rcp_f32_e32 v241, v241
	v_rcp_f32_e32 v242, v242
	v_rcp_f32_e32 v243, v243
	v_rcp_f32_e32 v244, v244
	v_rcp_f32_e32 v245, v245
	v_rcp_f32_e32 v246, v246
	v_rcp_f32_e32 v247, v247
	s_nop 0
	v_pk_mul_f32 v[232:233], v[136:137], v[232:233]
	v_pk_mul_f32 v[234:235], v[138:139], v[234:235]
	v_pk_mul_f32 v[236:237], v[140:141], v[236:237]
	v_pk_mul_f32 v[238:239], v[142:143], v[238:239]
	v_pk_mul_f32 v[240:241], v[144:145], v[240:241]
	v_pk_mul_f32 v[242:243], v[146:147], v[242:243]
	v_pk_mul_f32 v[244:245], v[148:149], v[244:245]
	v_pk_mul_f32 v[246:247], v[150:151], v[246:247]
	v_pk_mul_f32 v[232:233], v[232:233], v[170:171]
	v_pk_mul_f32 v[234:235], v[234:235], v[172:173]
	v_pk_mul_f32 v[236:237], v[236:237], v[174:175]
	v_pk_mul_f32 v[238:239], v[238:239], v[176:177]
	v_pk_mul_f32 v[240:241], v[240:241], v[178:179]
	v_pk_mul_f32 v[242:243], v[242:243], v[180:181]
	v_pk_mul_f32 v[244:245], v[244:245], v[182:183]
	v_pk_mul_f32 v[246:247], v[246:247], v[184:185]
	v_cvt_pk_bf16_f32 v152, v232, v233
	v_cvt_pk_bf16_f32 v153, v234, v235
	v_cvt_pk_bf16_f32 v156, v236, v237
	v_cvt_pk_bf16_f32 v157, v238, v239
	v_cvt_pk_bf16_f32 v154, v240, v241
	v_cvt_pk_bf16_f32 v155, v242, v243
	v_cvt_pk_bf16_f32 v158, v244, v245
	v_cvt_pk_bf16_f32 v159, v246, v247
	s_nop 1
	v_permlane32_swap_b32_e32 v152, v154
	v_permlane32_swap_b32_e32 v153, v155
	v_permlane32_swap_b32_e32 v156, v158
	v_permlane32_swap_b32_e32 v157, v159
	s_nop 1
	global_store_dwordx4 v[164:165], v[152:155], off offset:64
	global_store_dwordx4 v[164:165], v[156:159], off offset:80
	v_accvgpr_read_b32 v56, a160
	v_accvgpr_read_b32 v57, a161
	v_accvgpr_read_b32 v58, a162
	v_accvgpr_read_b32 v59, a163
	v_accvgpr_read_b32 v60, a164
	v_accvgpr_read_b32 v61, a165
	v_accvgpr_read_b32 v62, a166
	v_accvgpr_read_b32 v63, a167
	v_accvgpr_read_b32 v64, a168
	v_accvgpr_read_b32 v65, a169
	v_accvgpr_read_b32 v66, a170
	v_accvgpr_read_b32 v67, a171
	v_accvgpr_read_b32 v68, a172
	v_accvgpr_read_b32 v69, a173
	v_accvgpr_read_b32 v70, a174
	v_accvgpr_read_b32 v71, a175
	v_pk_mul_f32 v[120:121], v[56:57], v[186:187]
	v_pk_mul_f32 v[122:123], v[58:59], v[186:187]
	v_pk_mul_f32 v[124:125], v[60:61], v[186:187]
	v_pk_mul_f32 v[126:127], v[62:63], v[186:187]
	v_pk_mul_f32 v[128:129], v[64:65], v[186:187]
	v_pk_mul_f32 v[130:131], v[66:67], v[186:187]
	v_pk_mul_f32 v[132:133], v[68:69], v[186:187]
	v_pk_mul_f32 v[134:135], v[70:71], v[186:187]
	v_accvgpr_read_b32 v72, a16
	v_accvgpr_read_b32 v73, a17
	v_accvgpr_read_b32 v74, a18
	v_accvgpr_read_b32 v75, a19
	v_accvgpr_read_b32 v76, a20
	v_accvgpr_read_b32 v77, a21
	v_accvgpr_read_b32 v78, a22
	v_accvgpr_read_b32 v79, a23
	v_accvgpr_read_b32 v80, a24
	v_accvgpr_read_b32 v81, a25
	v_accvgpr_read_b32 v82, a26
	v_accvgpr_read_b32 v83, a27
	v_accvgpr_read_b32 v84, a28
	v_accvgpr_read_b32 v85, a29
	v_accvgpr_read_b32 v86, a30
	v_accvgpr_read_b32 v87, a31
	v_exp_f32_e32 v120, v120
	v_exp_f32_e32 v121, v121
	v_exp_f32_e32 v122, v122
	v_exp_f32_e32 v123, v123
	v_exp_f32_e32 v124, v124
	v_exp_f32_e32 v125, v125
	v_exp_f32_e32 v126, v126
	v_exp_f32_e32 v127, v127
	v_exp_f32_e32 v128, v128
	v_exp_f32_e32 v129, v129
	v_exp_f32_e32 v130, v130
	v_exp_f32_e32 v131, v131
	v_exp_f32_e32 v132, v132
	v_exp_f32_e32 v133, v133
	v_exp_f32_e32 v134, v134
	v_exp_f32_e32 v135, v135
	s_nop 0
	v_pk_add_f32 v[120:121], v[120:121], 1.0 op_sel_hi:[1,0]
	v_pk_add_f32 v[122:123], v[122:123], 1.0 op_sel_hi:[1,0]
	v_pk_add_f32 v[124:125], v[124:125], 1.0 op_sel_hi:[1,0]
	v_pk_add_f32 v[126:127], v[126:127], 1.0 op_sel_hi:[1,0]
	v_pk_add_f32 v[128:129], v[128:129], 1.0 op_sel_hi:[1,0]
	v_pk_add_f32 v[130:131], v[130:131], 1.0 op_sel_hi:[1,0]
	v_pk_add_f32 v[132:133], v[132:133], 1.0 op_sel_hi:[1,0]
	v_pk_add_f32 v[134:135], v[134:135], 1.0 op_sel_hi:[1,0]
	v_rcp_f32_e32 v120, v120
	v_rcp_f32_e32 v121, v121
	v_rcp_f32_e32 v122, v122
	v_rcp_f32_e32 v123, v123
	v_rcp_f32_e32 v124, v124
	v_rcp_f32_e32 v125, v125
	v_rcp_f32_e32 v126, v126
	v_rcp_f32_e32 v127, v127
	v_rcp_f32_e32 v128, v128
	v_rcp_f32_e32 v129, v129
	v_rcp_f32_e32 v130, v130
	v_rcp_f32_e32 v131, v131
	v_rcp_f32_e32 v132, v132
	v_rcp_f32_e32 v133, v133
	v_rcp_f32_e32 v134, v134
	v_rcp_f32_e32 v135, v135
	s_nop 0
	v_pk_mul_f32 v[120:121], v[56:57], v[120:121]
	v_pk_mul_f32 v[122:123], v[58:59], v[122:123]
	v_pk_mul_f32 v[124:125], v[60:61], v[124:125]
	v_pk_mul_f32 v[126:127], v[62:63], v[126:127]
	v_pk_mul_f32 v[128:129], v[64:65], v[128:129]
	v_pk_mul_f32 v[130:131], v[66:67], v[130:131]
	v_pk_mul_f32 v[132:133], v[68:69], v[132:133]
	v_pk_mul_f32 v[134:135], v[70:71], v[134:135]
	v_pk_mul_f32 v[120:121], v[120:121], v[72:73]
	v_pk_mul_f32 v[122:123], v[122:123], v[74:75]
	v_pk_mul_f32 v[124:125], v[124:125], v[76:77]
	v_pk_mul_f32 v[126:127], v[126:127], v[78:79]
	v_pk_mul_f32 v[128:129], v[128:129], v[80:81]
	v_pk_mul_f32 v[130:131], v[130:131], v[82:83]
	v_pk_mul_f32 v[132:133], v[132:133], v[84:85]
	v_pk_mul_f32 v[134:135], v[134:135], v[86:87]
	v_cvt_pk_bf16_f32 v88, v120, v121
	v_cvt_pk_bf16_f32 v89, v122, v123
	v_cvt_pk_bf16_f32 v92, v124, v125
	v_cvt_pk_bf16_f32 v93, v126, v127
	v_cvt_pk_bf16_f32 v90, v128, v129
	v_cvt_pk_bf16_f32 v91, v130, v131
	v_cvt_pk_bf16_f32 v94, v132, v133
	v_cvt_pk_bf16_f32 v95, v134, v135
	s_nop 1
	v_permlane32_swap_b32_e32 v88, v90
	v_permlane32_swap_b32_e32 v89, v91
	v_permlane32_swap_b32_e32 v92, v94
	v_permlane32_swap_b32_e32 v93, v95
	s_nop 1
	global_store_dwordx4 v[166:167], v[88:91], off offset:64
	global_store_dwordx4 v[166:167], v[92:95], off offset:80
	v_accvgpr_read_b32 v136, a176
	v_accvgpr_read_b32 v137, a177
	v_accvgpr_read_b32 v138, a178
	v_accvgpr_read_b32 v139, a179
	v_accvgpr_read_b32 v140, a180
	v_accvgpr_read_b32 v141, a181
	v_accvgpr_read_b32 v142, a182
	v_accvgpr_read_b32 v143, a183
	v_accvgpr_read_b32 v144, a184
	v_accvgpr_read_b32 v145, a185
	v_accvgpr_read_b32 v146, a186
	v_accvgpr_read_b32 v147, a187
	v_accvgpr_read_b32 v148, a188
	v_accvgpr_read_b32 v149, a189
	v_accvgpr_read_b32 v150, a190
	v_accvgpr_read_b32 v151, a191
	v_pk_mul_f32 v[232:233], v[136:137], v[186:187]
	v_pk_mul_f32 v[234:235], v[138:139], v[186:187]
	v_pk_mul_f32 v[236:237], v[140:141], v[186:187]
	v_pk_mul_f32 v[238:239], v[142:143], v[186:187]
	v_pk_mul_f32 v[240:241], v[144:145], v[186:187]
	v_pk_mul_f32 v[242:243], v[146:147], v[186:187]
	v_pk_mul_f32 v[244:245], v[148:149], v[186:187]
	v_pk_mul_f32 v[246:247], v[150:151], v[186:187]
	v_accvgpr_read_b32 v170, a0
	v_accvgpr_read_b32 v171, a1
	v_accvgpr_read_b32 v172, a2
	v_accvgpr_read_b32 v173, a3
	v_accvgpr_read_b32 v174, a4
	v_accvgpr_read_b32 v175, a5
	v_accvgpr_read_b32 v176, a6
	v_accvgpr_read_b32 v177, a7
	v_accvgpr_read_b32 v178, a8
	v_accvgpr_read_b32 v179, a9
	v_accvgpr_read_b32 v180, a10
	v_accvgpr_read_b32 v181, a11
	v_accvgpr_read_b32 v182, a12
	v_accvgpr_read_b32 v183, a13
	v_accvgpr_read_b32 v184, a14
	v_accvgpr_read_b32 v185, a15
	v_exp_f32_e32 v232, v232
	v_exp_f32_e32 v233, v233
	v_exp_f32_e32 v234, v234
	v_exp_f32_e32 v235, v235
	v_exp_f32_e32 v236, v236
	v_exp_f32_e32 v237, v237
	v_exp_f32_e32 v238, v238
	v_exp_f32_e32 v239, v239
	v_exp_f32_e32 v240, v240
	v_exp_f32_e32 v241, v241
	v_exp_f32_e32 v242, v242
	v_exp_f32_e32 v243, v243
	v_exp_f32_e32 v244, v244
	v_exp_f32_e32 v245, v245
	v_exp_f32_e32 v246, v246
	v_exp_f32_e32 v247, v247
	s_nop 0
	v_pk_add_f32 v[232:233], v[232:233], 1.0 op_sel_hi:[1,0]
	v_pk_add_f32 v[234:235], v[234:235], 1.0 op_sel_hi:[1,0]
	v_pk_add_f32 v[236:237], v[236:237], 1.0 op_sel_hi:[1,0]
	v_pk_add_f32 v[238:239], v[238:239], 1.0 op_sel_hi:[1,0]
	v_pk_add_f32 v[240:241], v[240:241], 1.0 op_sel_hi:[1,0]
	v_pk_add_f32 v[242:243], v[242:243], 1.0 op_sel_hi:[1,0]
	v_pk_add_f32 v[244:245], v[244:245], 1.0 op_sel_hi:[1,0]
	v_pk_add_f32 v[246:247], v[246:247], 1.0 op_sel_hi:[1,0]
	v_rcp_f32_e32 v232, v232
	v_rcp_f32_e32 v233, v233
	v_rcp_f32_e32 v234, v234
	v_rcp_f32_e32 v235, v235
	v_rcp_f32_e32 v236, v236
	v_rcp_f32_e32 v237, v237
	v_rcp_f32_e32 v238, v238
	v_rcp_f32_e32 v239, v239
	v_rcp_f32_e32 v240, v240
	v_rcp_f32_e32 v241, v241
	v_rcp_f32_e32 v242, v242
	v_rcp_f32_e32 v243, v243
	v_rcp_f32_e32 v244, v244
	v_rcp_f32_e32 v245, v245
	v_rcp_f32_e32 v246, v246
	v_rcp_f32_e32 v247, v247
	s_nop 0
	v_pk_mul_f32 v[232:233], v[136:137], v[232:233]
	v_pk_mul_f32 v[234:235], v[138:139], v[234:235]
	v_pk_mul_f32 v[236:237], v[140:141], v[236:237]
	v_pk_mul_f32 v[238:239], v[142:143], v[238:239]
	v_pk_mul_f32 v[240:241], v[144:145], v[240:241]
	v_pk_mul_f32 v[242:243], v[146:147], v[242:243]
	v_pk_mul_f32 v[244:245], v[148:149], v[244:245]
	v_pk_mul_f32 v[246:247], v[150:151], v[246:247]
	v_pk_mul_f32 v[232:233], v[232:233], v[170:171]
	v_pk_mul_f32 v[234:235], v[234:235], v[172:173]
	v_pk_mul_f32 v[236:237], v[236:237], v[174:175]
	v_pk_mul_f32 v[238:239], v[238:239], v[176:177]
	v_pk_mul_f32 v[240:241], v[240:241], v[178:179]
	v_pk_mul_f32 v[242:243], v[242:243], v[180:181]
	v_pk_mul_f32 v[244:245], v[244:245], v[182:183]
	v_pk_mul_f32 v[246:247], v[246:247], v[184:185]
	v_cvt_pk_bf16_f32 v152, v232, v233
	v_cvt_pk_bf16_f32 v153, v234, v235
	v_cvt_pk_bf16_f32 v156, v236, v237
	v_cvt_pk_bf16_f32 v157, v238, v239
	v_cvt_pk_bf16_f32 v154, v240, v241
	v_cvt_pk_bf16_f32 v155, v242, v243
	v_cvt_pk_bf16_f32 v158, v244, v245
	v_cvt_pk_bf16_f32 v159, v246, v247
	s_nop 1
	v_permlane32_swap_b32_e32 v152, v154
	v_permlane32_swap_b32_e32 v153, v155
	v_permlane32_swap_b32_e32 v156, v158
	v_permlane32_swap_b32_e32 v157, v159
	s_nop 1
	global_store_dwordx4 v[168:169], v[152:155], off offset:64
	global_store_dwordx4 v[168:169], v[156:159], off offset:80
	s_branch .Lgu_partB

.Lgu_partB:
	v_accvgpr_mov_b32 a193, a192
	v_accvgpr_mov_b32 a194, a192
	v_accvgpr_mov_b32 a195, a192
	v_accvgpr_mov_b32 a196, a192
	v_accvgpr_mov_b32 a197, a192
	v_accvgpr_mov_b32 a198, a192
	v_accvgpr_mov_b32 a199, a192
	v_accvgpr_mov_b32 a200, a192
	v_accvgpr_mov_b32 a201, a192
	v_accvgpr_mov_b32 a202, a192
	v_accvgpr_mov_b32 a203, a192
	v_accvgpr_mov_b32 a204, a192
	v_accvgpr_mov_b32 a205, a192
	v_accvgpr_mov_b32 a206, a192
	v_accvgpr_mov_b32 a207, a192
	v_accvgpr_mov_b32 a0, a192
	v_accvgpr_mov_b32 a16, a192
	v_accvgpr_mov_b32 a32, a192
	v_accvgpr_write_b32 a95, 0
	v_accvgpr_write_b32 a94, 0
	v_accvgpr_write_b32 a93, 0
	v_accvgpr_write_b32 a92, 0
	v_accvgpr_write_b32 a91, 0
	v_accvgpr_write_b32 a90, 0
	v_accvgpr_write_b32 a89, 0
	v_accvgpr_write_b32 a88, 0
	v_accvgpr_write_b32 a87, 0
	v_accvgpr_write_b32 a86, 0
	v_accvgpr_write_b32 a85, 0
	v_accvgpr_write_b32 a84, 0
	v_accvgpr_write_b32 a83, 0
	v_accvgpr_write_b32 a82, 0
	v_accvgpr_write_b32 a81, 0
	v_accvgpr_write_b32 a80, 0
	v_accvgpr_write_b32 a63, 0
	v_accvgpr_write_b32 a62, 0
	v_accvgpr_write_b32 a61, 0
	v_accvgpr_write_b32 a60, 0
	v_accvgpr_write_b32 a59, 0
	v_accvgpr_write_b32 a58, 0
	v_accvgpr_write_b32 a57, 0
	v_accvgpr_write_b32 a56, 0
	v_accvgpr_write_b32 a55, 0
	v_accvgpr_write_b32 a54, 0
	v_accvgpr_write_b32 a53, 0
	v_accvgpr_write_b32 a52, 0
	v_accvgpr_write_b32 a51, 0
	v_accvgpr_write_b32 a50, 0
	v_accvgpr_write_b32 a49, 0
	v_accvgpr_write_b32 a48, 0
	v_accvgpr_write_b32 a79, 0
	v_accvgpr_write_b32 a78, 0
	v_accvgpr_write_b32 a77, 0
	v_accvgpr_write_b32 a76, 0
	v_accvgpr_write_b32 a75, 0
	v_accvgpr_write_b32 a74, 0
	v_accvgpr_write_b32 a73, 0
	v_accvgpr_write_b32 a72, 0
	v_accvgpr_write_b32 a71, 0
	v_accvgpr_write_b32 a70, 0
	v_accvgpr_write_b32 a69, 0
	v_accvgpr_write_b32 a68, 0
	v_accvgpr_write_b32 a67, 0
	v_accvgpr_write_b32 a66, 0
	v_accvgpr_write_b32 a65, 0
	v_accvgpr_write_b32 a64, 0
	v_accvgpr_write_b32 a111, 0
	v_accvgpr_write_b32 a110, 0
	v_accvgpr_write_b32 a109, 0
	v_accvgpr_write_b32 a108, 0
	v_accvgpr_write_b32 a107, 0
	v_accvgpr_write_b32 a106, 0
	v_accvgpr_write_b32 a105, 0
	v_accvgpr_write_b32 a104, 0
	v_accvgpr_write_b32 a103, 0
	v_accvgpr_write_b32 a102, 0
	v_accvgpr_write_b32 a101, 0
	v_accvgpr_write_b32 a100, 0
	v_accvgpr_write_b32 a99, 0
	v_accvgpr_write_b32 a98, 0
	v_accvgpr_write_b32 a97, 0
	v_accvgpr_write_b32 a96, 0
	v_accvgpr_write_b32 a127, 0
	v_accvgpr_write_b32 a126, 0
	v_accvgpr_write_b32 a125, 0
	v_accvgpr_write_b32 a124, 0
	v_accvgpr_write_b32 a123, 0
	v_accvgpr_write_b32 a122, 0
	v_accvgpr_write_b32 a121, 0
	v_accvgpr_write_b32 a120, 0
	v_accvgpr_write_b32 a119, 0
	v_accvgpr_write_b32 a118, 0
	v_accvgpr_write_b32 a117, 0
	v_accvgpr_write_b32 a116, 0
	v_accvgpr_write_b32 a115, 0
	v_accvgpr_write_b32 a114, 0
	v_accvgpr_write_b32 a113, 0
	v_accvgpr_write_b32 a112, 0
	v_accvgpr_write_b32 a143, 0
	v_accvgpr_write_b32 a142, 0
	v_accvgpr_write_b32 a141, 0
	v_accvgpr_write_b32 a140, 0
	v_accvgpr_write_b32 a139, 0
	v_accvgpr_write_b32 a138, 0
	v_accvgpr_write_b32 a137, 0
	v_accvgpr_write_b32 a136, 0
	v_accvgpr_write_b32 a135, 0
	v_accvgpr_write_b32 a134, 0
	v_accvgpr_write_b32 a133, 0
	v_accvgpr_write_b32 a132, 0
	v_accvgpr_write_b32 a131, 0
	v_accvgpr_write_b32 a130, 0
	v_accvgpr_write_b32 a129, 0
	v_accvgpr_write_b32 a128, 0
	v_accvgpr_write_b32 a159, 0
	v_accvgpr_write_b32 a158, 0
	v_accvgpr_write_b32 a157, 0
	v_accvgpr_write_b32 a156, 0
	v_accvgpr_write_b32 a155, 0
	v_accvgpr_write_b32 a154, 0
	v_accvgpr_write_b32 a153, 0
	v_accvgpr_write_b32 a152, 0
	v_accvgpr_write_b32 a151, 0
	v_accvgpr_write_b32 a150, 0
	v_accvgpr_write_b32 a149, 0
	v_accvgpr_write_b32 a148, 0
	v_accvgpr_write_b32 a147, 0
	v_accvgpr_write_b32 a146, 0
	v_accvgpr_write_b32 a145, 0
	v_accvgpr_write_b32 a144, 0
	v_accvgpr_write_b32 a175, 0
	v_accvgpr_write_b32 a174, 0
	v_accvgpr_write_b32 a173, 0
	v_accvgpr_write_b32 a172, 0
	v_accvgpr_write_b32 a171, 0
	v_accvgpr_write_b32 a170, 0
	v_accvgpr_write_b32 a169, 0
	v_accvgpr_write_b32 a168, 0
	v_accvgpr_write_b32 a167, 0
	v_accvgpr_write_b32 a166, 0
	v_accvgpr_write_b32 a165, 0
	v_accvgpr_write_b32 a164, 0
	v_accvgpr_write_b32 a163, 0
	v_accvgpr_write_b32 a162, 0
	v_accvgpr_write_b32 a161, 0
	v_accvgpr_write_b32 a160, 0
	v_accvgpr_write_b32 a191, 0
	v_accvgpr_write_b32 a190, 0
	v_accvgpr_write_b32 a189, 0
	v_accvgpr_write_b32 a188, 0
	v_accvgpr_write_b32 a187, 0
	v_accvgpr_write_b32 a186, 0
	v_accvgpr_write_b32 a185, 0
	v_accvgpr_write_b32 a184, 0
	v_accvgpr_write_b32 a183, 0
	v_accvgpr_write_b32 a182, 0
	v_accvgpr_write_b32 a181, 0
	v_accvgpr_write_b32 a180, 0
	v_accvgpr_write_b32 a179, 0
	v_accvgpr_write_b32 a178, 0
	v_accvgpr_write_b32 a177, 0
	v_accvgpr_write_b32 a176, 0
	v_accvgpr_mov_b32 a1, a193
	v_accvgpr_mov_b32 a2, a194
	v_accvgpr_mov_b32 a3, a195
	v_accvgpr_mov_b32 a4, a196
	v_accvgpr_mov_b32 a5, a197
	v_accvgpr_mov_b32 a6, a198
	v_accvgpr_mov_b32 a7, a199
	v_accvgpr_mov_b32 a8, a200
	v_accvgpr_mov_b32 a9, a201
	v_accvgpr_mov_b32 a10, a202
	v_accvgpr_mov_b32 a11, a203
	v_accvgpr_mov_b32 a12, a204
	v_accvgpr_mov_b32 a13, a205
	v_accvgpr_mov_b32 a14, a206
	v_accvgpr_mov_b32 a15, a207
	v_accvgpr_mov_b32 a17, a193
	v_accvgpr_mov_b32 a18, a194
	v_accvgpr_mov_b32 a19, a195
	v_accvgpr_mov_b32 a20, a196
	v_accvgpr_mov_b32 a21, a197
	v_accvgpr_mov_b32 a22, a198
	v_accvgpr_mov_b32 a23, a199
	v_accvgpr_mov_b32 a24, a200
	v_accvgpr_mov_b32 a25, a201
	v_accvgpr_mov_b32 a26, a202
	v_accvgpr_mov_b32 a27, a203
	v_accvgpr_mov_b32 a28, a204
	v_accvgpr_mov_b32 a29, a205
	v_accvgpr_mov_b32 a30, a206
	v_accvgpr_mov_b32 a31, a207
	v_accvgpr_mov_b32 a33, a193
	v_accvgpr_mov_b32 a34, a194
	v_accvgpr_mov_b32 a35, a195
	v_accvgpr_mov_b32 a36, a196
	v_accvgpr_mov_b32 a37, a197
	v_accvgpr_mov_b32 a38, a198
	v_accvgpr_mov_b32 a39, a199
	v_accvgpr_mov_b32 a40, a200
	v_accvgpr_mov_b32 a41, a201
	v_accvgpr_mov_b32 a42, a202
	v_accvgpr_mov_b32 a43, a203
	v_accvgpr_mov_b32 a44, a204
	v_accvgpr_mov_b32 a45, a205
	v_accvgpr_mov_b32 a46, a206
	v_accvgpr_mov_b32 a47, a207
	s_waitcnt vmcnt(13)
	ds_write_b128 v118, v[0:3] offset:0
	s_waitcnt vmcnt(12)
	ds_write_b128 v118, v[32:35] offset:0x1000
	s_waitcnt vmcnt(11)
	ds_write_b128 v118, v[36:39] offset:0x2000
	s_mov_b64 s[8:9], 0x20000
	s_mov_b64 s[6:7], 0x40000
	s_mov_b64 s[10:11], 0x60000
	s_waitcnt vmcnt(10)
	ds_write_b128 v118, v[40:43] offset:0x3000
	s_waitcnt vmcnt(9)
	ds_write_b128 v118, v[44:47] offset:0x4000
	s_waitcnt vmcnt(8)
	ds_write_b128 v118, v[48:51] offset:0x5000
	s_waitcnt vmcnt(7)
	ds_write_b128 v118, v[52:55] offset:0x6000
	s_waitcnt lgkmcnt(0)
	v_mov_b32_e32 v0, 0
	v_lshl_add_u64 v[100:101], v[96:97], 0, s[8:9]
	s_mov_b32 s4, 0
	v_lshl_add_u64 v[102:103], v[96:97], 0, s[6:7]
	v_lshl_add_u64 v[104:105], v[96:97], 0, s[10:11]
	v_lshl_add_u64 v[106:107], v[98:99], 0, s[8:9]
	v_lshl_add_u64 v[108:109], v[98:99], 0, s[6:7]
	s_mov_b32 s3, -2
	v_mov_b32_e32 v1, v0
	v_mov_b32_e32 v2, v0
	v_mov_b32_e32 v3, v0
	v_mov_b32_e32 v128, v0
	v_mov_b32_e32 v129, v0
	v_mov_b32_e32 v130, v0
	v_mov_b32_e32 v131, v0
	v_mov_b32_e32 v32, v0
	v_mov_b32_e32 v33, v0
	v_mov_b32_e32 v34, v0
	v_mov_b32_e32 v35, v0
	s_barrier
